# ssd_out: next-unit decay factors computed in the loop latch instead of behind vmcnt(7)/(6) right after the prefetch loads (removes a mid-unit exposed memory latency)
# baseline (speedup 1.0000x reference)
.LBB0_439:
	s_lshl_b32 s68, s86, 7
	s_add_u32 s82, s88, s68
	v_add_u32_e32 v136, s90, v169
	v_mov_b32_e32 v137, v145
	s_addc_u32 s83, s89, 0
	v_lshlrev_b64 v[136:137], 10, v[136:137]
	v_lshl_add_u64 v[136:137], s[82:83], 0, v[136:137]
	v_pk_add_f32 v[114:115], v[122:123], v[114:115]
	v_pk_add_f32 v[112:113], v[120:121], v[112:113]
	v_lshl_add_u64 v[136:137], v[150:151], 1, v[136:137]
	v_cvt_pk_bf16_f32 v112, v112, v113
	v_cvt_pk_bf16_f32 v113, v114, v115
	global_store_dwordx2 v[136:137], v[112:113], off
	v_pk_add_f32 v[112:113], v[126:127], v[118:119]
	v_pk_add_f32 v[114:115], v[124:125], v[116:117]
	v_pk_add_f32 v[110:111], v[130:131], v[110:111]
	v_pk_add_f32 v[108:109], v[128:129], v[108:109]
	v_pk_add_f32 v[106:107], v[134:135], v[106:107]
	v_pk_add_f32 v[104:105], v[132:133], v[104:105]
	v_cvt_pk_bf16_f32 v114, v114, v115
	v_cvt_pk_bf16_f32 v115, v112, v113
	v_cvt_pk_bf16_f32 v108, v108, v109
	v_cvt_pk_bf16_f32 v109, v110, v111
	v_cvt_pk_bf16_f32 v104, v104, v105
	v_cvt_pk_bf16_f32 v105, v106, v107
	s_xor_b32 s70, s70, 1
	s_add_i32 s85, s85, 1
	s_andn2_b64 vcc, exec, s[80:81]
	s_mov_b32 s90, s87
	s_mov_b32 s86, s71
	global_store_dwordx2 v[136:137], v[114:115], off offset:32
	global_store_dwordx2 v[136:137], v[108:109], off offset:64
	global_store_dwordx2 v[136:137], v[104:105], off offset:96
	s_waitcnt vmcnt(14)
	v_mul_f32_e32 v170, 0x3fb8aa3b, v170
	v_mul_f32_e32 v171, 0x3fb8aa3b, v171
	v_exp_f32_e32 v170, v170
	v_exp_f32_e32 v171, v171
	s_nop 0
	v_xor_b32_e32 v178, 0x80000000, v170
	v_xor_b32_e32 v182, 0x80000000, v171
	s_cbranch_vccz .LBB0_595

.LBB0_444:
	s_lshr_b32 s68, s85, 2
	s_mul_i32 s68, s68, s94
	v_readlane_b32 s0, v253, 34
	s_add_i32 s68, s68, s0
	s_lshl_b32 s71, s68, 2
	s_and_b32 s92, s85, 3
	s_or_b32 s71, s71, s92
	s_cmpk_lt_i32 s68, 0x300
	s_cselect_b32 s93, s71, -1
	s_cmp_lt_i32 s93, 0
	s_cselect_b64 s[80:81], -1, 0
	s_and_b64 vcc, exec, s[80:81]
	s_cbranch_vccnz .LBB0_450
	s_and_b32 s71, s93, 7
	s_lshl_b32 s68, s71, 2
	v_readlane_b32 s8, v253, 0
	v_mov_b32_e32 v32, s68
	v_readlane_b32 s20, v253, 12
	v_readlane_b32 s21, v253, 13
	s_nop 4
	global_load_dword v170, v32, s[20:21]
	global_load_dword v171, v32, s[20:21] offset:32
	s_mov_b32 s4, s97
	s_mov_b32 s58, s96
	v_readlane_b32 s96, v253, 39
	s_mov_b64 s[0:1], s[94:95]
	s_lshr_b32 s94, s93, 3
	v_readlane_b32 s97, v253, 40
	s_and_b64 vcc, exec, s[96:97]
	s_lshl_b32 s87, s94, 7
	v_readlane_b32 s9, v253, 1
	v_readlane_b32 s10, v253, 2
	v_readlane_b32 s11, v253, 3
	v_readlane_b32 s12, v253, 4
	v_readlane_b32 s13, v253, 5
	v_readlane_b32 s14, v253, 6
	v_readlane_b32 s15, v253, 7
	v_readlane_b32 s16, v253, 8
	v_readlane_b32 s17, v253, 9
	v_readlane_b32 s18, v253, 10
	v_readlane_b32 s19, v253, 11
	v_readlane_b32 s22, v253, 14
	v_readlane_b32 s23, v253, 15
	s_cbranch_vccnz .LBB0_447
	v_add_u32_e32 v32, s87, v162
	v_ashrrev_i32_e32 v33, 31, v32
	v_readlane_b32 s8, v253, 35
	v_lshlrev_b64 v[32:33], 6, v[32:33]
	v_readlane_b32 s9, v253, 36
	s_nop 1
	v_lshl_add_u64 v[32:33], s[8:9], 0, v[32:33]
	v_lshl_add_u64 v[32:33], v[32:33], 0, s[68:69]
	global_load_dword v140, v[32:33], off
	global_load_dword v142, v[32:33], off offset:32
	global_load_dword v141, v[32:33], off offset:64
	global_load_dword v143, v[32:33], off offset:96

.LBB0_449:
	s_mov_b64 s[94:95], s[0:1]
	s_mov_b32 s96, s58
	s_mov_b32 s97, s4
	s_branch .LBB0_451
